# same as best plus s_nop hazard padding between v_writelane and v_readlane of v255 in the P2 stage-order code
# baseline (speedup 1.0000x reference)
; __device__ __forceinline__ int fresh_tid() { int t = threadIdx.x; asm volatile("" : "+v"(t)); return t; }
; __global__ void __launch_bounds__(NTHR) fwd_megakernel(P p) {
;     ...
;         { const int t0 = fresh_tid(); const int w = __builtin_amdgcn_readfirstlane(t0 >> 6);
;           __syncthreads();
;           if (w < 4) { for (int wi = w * G + blockIdx.x; wi < 1024; wi += G * 4) attn_sample_item(p, wi, t0 & 63); }
;           else side_transposes(p, lds, w - 4, t0 & 63, G); }
;         for (int rep = 0; rep < NREP(16); ++rep) { const int t0 = fresh_tid(); for (int it = blockIdx.x; it < 256; it += G) gla_sample_item(p, lds, it, t0); }
;         for (int rep = 0; rep < NREP(32); ++rep) { const int t0 = fresh_tid(); for (int it = blockIdx.x; it < 512; it += G) gla_a_item(p, lds, it, t0); }
;         for (int rep = 0; rep < NREP(64); ++rep) attn_prompt_loop(p, lds, fresh_tid(), G);
.LBB0_530:
	v_readlane_b32 s74, v255, 1
	v_readlane_b32 s75, v255, 2
	s_cmp_eq_u32 s98, 1
	s_cbranch_scc0 .LBB0_531
	v_writelane_b32 v255, s0, 40
	v_writelane_b32 v255, s1, 41
	v_writelane_b32 v255, s16, 42
	v_writelane_b32 v255, s17, 43
	v_writelane_b32 v255, s21, 44
	v_writelane_b32 v255, s24, 45
	v_writelane_b32 v255, s25, 46
	v_writelane_b32 v255, s28, 47
	v_writelane_b32 v255, s29, 48
	v_writelane_b32 v255, s42, 49
	v_writelane_b32 v255, s43, 50
	v_writelane_b32 v255, s44, 51
	v_writelane_b32 v255, s45, 52
	v_writelane_b32 v255, s46, 53
	v_writelane_b32 v255, s47, 54
	v_writelane_b32 v255, s62, 55
	v_writelane_b32 v255, s74, 56
	v_writelane_b32 v255, s91, 57
	v_writelane_b32 v255, s94, 58
	v_writelane_b32 v255, s95, 59
	v_writelane_b32 v255, s96, 60
	v_writelane_b32 v255, s97, 61
	s_nop 1
	v_readlane_b32 s8, v255, 24
	v_readlane_b32 s9, v255, 25
	v_readlane_b32 s10, v255, 26
	v_readlane_b32 s11, v255, 27
	v_readlane_b32 s42, v255, 28
	v_readlane_b32 s43, v255, 29
	v_readlane_b32 s44, v255, 30
	v_readlane_b32 s45, v255, 31
	v_readlane_b32 s46, v255, 32
	v_readlane_b32 s47, v255, 33
	v_readlane_b32 s48, v255, 34
	v_readlane_b32 s49, v255, 35
	v_readlane_b32 s56, v255, 36
	v_readlane_b32 s57, v255, 37
	v_readlane_b32 s58, v255, 38
	v_readlane_b32 s59, v255, 39
	v_mov_b32_e32 v42, v230
	s_mov_b32 s98, 2
	s_waitcnt vmcnt(0) lgkmcnt(0)
	s_branch .Lp2_hstage
